# a22 plus relaxed vmcnt(16) in the first two super-phases of FFN1 tiles that follow an epilogue (8 stores still in flight)
# baseline (speedup 1.0000x reference)
; #define PG8_STAGE(bufoff, gbase, voff) do { _Pragma("unroll") for (int _i = 0; _i < 2; ++_i) \
;         __builtin_amdgcn_global_load_lds((const unsigned*)((const char*)(gbase) + (voff)[_i]), (PG8_LAS unsigned*)(lds + (bufoff) + ldsw + _i * 8192), 16, 0, 0); } while (0)
; #define PG8_LDA(dst, b, h) do { _Pragma("unroll") for (int m = 0; m < 4; ++m) _Pragma("unroll") for (int k = 0; k < 2; ++k) dst[m][k] = *(const PG8_LAS bf16x8*)(lds + PG8_SA(b, h) + aoff + m * 2048 + k * 1024); } while (0)
; #define PG8_LDB(dst, b, h) do { _Pragma("unroll") for (int n = 0; n < 2; ++n) _Pragma("unroll") for (int k = 0; k < 2; ++k) dst[n][k] = *(const PG8_LAS bf16x8*)(lds + PG8_SB(b, h) + boff + n * 2048 + k * 1024); } while (0)
; #define PG8_MMA(ai, bj, At, Bt) do { __builtin_amdgcn_s_setprio(1); _Pragma("unroll") for (int m = 0; m < 4; ++m) _Pragma("unroll") for (int n = 0; n < 2; ++n) _Pragma("unroll") for (int k = 0; k < 2; ++k) \
;         acc[ai][bj][m][n] = __builtin_amdgcn_mfma_f32_16x16x32_bf16(Bt[n][k], At[m][k], acc[ai][bj][m][n], 0, 0, 0); __builtin_amdgcn_s_setprio(0); } while (0)
; #define PG8_WAIT_V(n) asm volatile("s_waitcnt vmcnt(" #n ")" ::: "memory")
; #define PG8_BAR __builtin_amdgcn_s_barrier()
; template <class Epi, class Sched, bool ALIGN_EPI = false, bool SP2 = false>
; __device__ __forceinline__ void gemm_phase(PG8_LAS unsigned char* lds, const Gemm g, const Sched& S, const Epi& E) {
;     ...
;         for (int t = 0; t < nt; t += 2) {
;             const bool last = (t == nt - 2);
;             const char* a1 = cA + (size_t)(t + 1) * kstep;
;             const char* a2 = last ? nA : cA + (size_t)(t + 2) * kstep; const char* b2 = last ? nB : cB + (size_t)(t + 2) * kstep;
;             const char* a3 = a2 + kstep; const char* b3 = b2 + kstep;
;             if (last && has_next) S.a_ready(nxt);
;             if constexpr (SP2) {
;             PG8_LDB(B0, 0, 0); PG8_LDB(B1, 0, 1); PG8_SCHED; PG8_LDA(At, 0, 0); PG8_STAGE(PG8_SA(1, 1), a1 + hstep, voffA);
;             PG8_WAIT_V(8); PG8_WAIT_L(0); PG8_BAR; PG8_MMA(0, 0, At, B0); PG8_MMA(0, 1, At, B1); PG8_BAR; PG8_SCHED;
;             PG8_LDA(At, 0, 1); PG8_STAGE(PG8_SB(0, 0), b2, voffB); PG8_STAGE(PG8_SB(0, 1), b2 + hstep, voffB); PG8_STAGE(PG8_SA(0, 0), a2, voffA);
;             PG8_WAIT_V(8); PG8_WAIT_L(0); PG8_BAR; PG8_MMA(1, 0, At, B0); PG8_MMA(1, 1, At, B1); PG8_BAR; PG8_SCHED;
.LBB0_401:
	s_add_u32 s31, s4, 0x100
	s_addc_u32 s41, s5, 0
	s_mov_b32 s43, -2
	s_cmp_lg_u32 s89, 1
	s_cbranch_scc1 .Lpeel_rlx_d
	s_add_u32 s36, s18, 0x100
	s_addc_u32 s37, s19, 0
	s_add_i32 s47, 0, 0x10000
	s_cmp_eq_u32 s43, 28
	s_cselect_b32 s39, s9, s37
	s_cselect_b32 s38, s8, s36
	s_cselect_b32 s5, s17, s41
	s_cselect_b32 s4, s16, s31
	s_add_i32 s92, 0, 0x14000
	v_add_u32_e32 v156, s47, v1
	v_add_u32_e32 v172, s92, v1
	ds_read_b128 v[144:147], v156
	ds_read_b128 v[148:151], v156 offset:1024
	ds_read_b128 v[152:155], v156 offset:2048
	ds_read_b128 v[156:159], v156 offset:3072
	ds_read_b128 v[160:163], v172
	ds_read_b128 v[164:167], v172 offset:1024
	ds_read_b128 v[168:171], v172 offset:2048
	ds_read_b128 v[172:175], v172 offset:3072
	s_add_i32 m0, s54, 0xc000
	ds_read_b128 v[176:179], v17
	ds_read_b128 v[180:183], v17 offset:1024
	ds_read_b128 v[184:187], v17 offset:2048
	ds_read_b128 v[188:191], v17 offset:3072
	ds_read_b128 v[192:195], v17 offset:4096
	ds_read_b128 v[196:199], v17 offset:5120
	ds_read_b128 v[200:203], v17 offset:6144
	ds_read_b128 v[204:207], v17 offset:7168
	global_load_lds_dwordx4 v142, s[18:19]
	s_add_i32 m0, s54, 0xe000
	s_nop 0
	global_load_lds_dwordx4 v140, s[18:19]
	s_waitcnt vmcnt(8)
	s_waitcnt lgkmcnt(0)
	s_barrier
	s_setprio 1
	s_waitcnt lgkmcnt(0)
	v_mfma_f32_16x16x32_bf16 v[130:133], v[144:147], v[176:179], 0
	v_mfma_f32_16x16x32_bf16 v[122:125], v[152:155], v[176:179], 0
	v_mfma_f32_16x16x32_bf16 v[114:117], v[144:147], v[184:187], 0
	v_mfma_f32_16x16x32_bf16 v[106:109], v[152:155], v[184:187], 0
	v_mfma_f32_16x16x32_bf16 v[98:101], v[144:147], v[192:195], 0
	v_mfma_f32_16x16x32_bf16 v[90:93], v[152:155], v[192:195], 0
	v_mfma_f32_16x16x32_bf16 v[82:85], v[144:147], v[200:203], 0
	v_mfma_f32_16x16x32_bf16 v[74:77], v[152:155], v[200:203], 0
	v_mfma_f32_16x16x32_bf16 v[130:133], v[148:151], v[180:183], v[130:133]
	v_mfma_f32_16x16x32_bf16 v[122:125], v[156:159], v[180:183], v[122:125]
	v_mfma_f32_16x16x32_bf16 v[114:117], v[148:151], v[188:191], v[114:117]
	v_mfma_f32_16x16x32_bf16 v[106:109], v[156:159], v[188:191], v[106:109]
	v_mfma_f32_16x16x32_bf16 v[98:101], v[148:151], v[196:199], v[98:101]
	v_mfma_f32_16x16x32_bf16 v[90:93], v[156:159], v[196:199], v[90:93]
	v_mfma_f32_16x16x32_bf16 v[82:85], v[148:151], v[204:207], v[82:85]
	v_mfma_f32_16x16x32_bf16 v[74:77], v[156:159], v[204:207], v[74:77]
	s_setprio 0
	s_setprio 1
	v_mfma_f32_16x16x32_bf16 v[126:129], v[160:163], v[176:179], 0
	v_mfma_f32_16x16x32_bf16 v[118:121], v[168:171], v[176:179], 0
	v_mfma_f32_16x16x32_bf16 v[110:113], v[160:163], v[184:187], 0
	v_mfma_f32_16x16x32_bf16 v[102:105], v[168:171], v[184:187], 0
	v_mfma_f32_16x16x32_bf16 v[94:97], v[160:163], v[192:195], 0
	v_mfma_f32_16x16x32_bf16 v[86:89], v[168:171], v[192:195], 0
	v_mfma_f32_16x16x32_bf16 v[78:81], v[160:163], v[200:203], 0
	v_mfma_f32_16x16x32_bf16 v[70:73], v[168:171], v[200:203], 0
	v_mfma_f32_16x16x32_bf16 v[126:129], v[164:167], v[180:183], v[126:129]
	v_mfma_f32_16x16x32_bf16 v[118:121], v[172:175], v[180:183], v[118:121]
	v_mfma_f32_16x16x32_bf16 v[110:113], v[164:167], v[188:191], v[110:113]
	v_mfma_f32_16x16x32_bf16 v[102:105], v[172:175], v[188:191], v[102:105]
	v_mfma_f32_16x16x32_bf16 v[94:97], v[164:167], v[196:199], v[94:97]
	v_mfma_f32_16x16x32_bf16 v[86:89], v[172:175], v[196:199], v[86:89]
	v_mfma_f32_16x16x32_bf16 v[78:81], v[164:167], v[204:207], v[78:81]
	v_mfma_f32_16x16x32_bf16 v[70:73], v[172:175], v[204:207], v[70:73]
	s_setprio 0
	s_barrier
	s_add_i32 s18, s47, s46
	s_mov_b32 m0, s18
	ds_read_b128 v[176:179], v17 offset:16384
	ds_read_b128 v[180:183], v17 offset:17408
	ds_read_b128 v[184:187], v17 offset:18432
	ds_read_b128 v[188:191], v17 offset:19456
	ds_read_b128 v[192:195], v17 offset:20480
	ds_read_b128 v[196:199], v17 offset:21504
	ds_read_b128 v[200:203], v17 offset:22528
	ds_read_b128 v[204:207], v17 offset:23552
	global_load_lds_dwordx4 v136, s[4:5]
	s_add_i32 m0, s18, 0x2000
	s_add_u32 s18, s4, 0x84000
	s_addc_u32 s19, s5, 0
	s_add_i32 s47, s92, s46
	global_load_lds_dwordx4 v14, s[4:5]
	s_mov_b32 m0, s47
	s_nop 0
	global_load_lds_dwordx4 v136, s[18:19]
	s_add_i32 m0, s47, 0x2000
	s_nop 0
	global_load_lds_dwordx4 v14, s[18:19]
	s_mov_b32 m0, s54
	s_nop 0
	global_load_lds_dwordx4 v138, s[38:39]
	s_mov_b32 m0, s64
	s_nop 0
	global_load_lds_dwordx4 v134, s[38:39]
	s_waitcnt vmcnt(8)
	s_waitcnt lgkmcnt(0)
	s_barrier
	s_setprio 1
	s_waitcnt lgkmcnt(0)
	v_mfma_f32_16x16x32_bf16 v[66:69], v[144:147], v[176:179], 0
	v_mfma_f32_16x16x32_bf16 v[58:61], v[152:155], v[176:179], 0
	v_mfma_f32_16x16x32_bf16 v[50:53], v[144:147], v[184:187], 0
	v_mfma_f32_16x16x32_bf16 v[42:45], v[152:155], v[184:187], 0
	v_mfma_f32_16x16x32_bf16 v[34:37], v[144:147], v[192:195], 0
	v_mfma_f32_16x16x32_bf16 v[26:29], v[152:155], v[192:195], 0
	v_mfma_f32_16x16x32_bf16 v[18:21], v[144:147], v[200:203], 0
	v_mfma_f32_16x16x32_bf16 v[6:9], v[152:155], v[200:203], 0
	v_mfma_f32_16x16x32_bf16 v[66:69], v[148:151], v[180:183], v[66:69]
	v_mfma_f32_16x16x32_bf16 v[58:61], v[156:159], v[180:183], v[58:61]
	v_mfma_f32_16x16x32_bf16 v[50:53], v[148:151], v[188:191], v[50:53]
	v_mfma_f32_16x16x32_bf16 v[42:45], v[156:159], v[188:191], v[42:45]
	v_mfma_f32_16x16x32_bf16 v[34:37], v[148:151], v[196:199], v[34:37]
	v_mfma_f32_16x16x32_bf16 v[26:29], v[156:159], v[196:199], v[26:29]
	v_mfma_f32_16x16x32_bf16 v[18:21], v[148:151], v[204:207], v[18:21]
	v_mfma_f32_16x16x32_bf16 v[6:9], v[156:159], v[204:207], v[6:9]
	s_setprio 0
	s_setprio 1
	v_mfma_f32_16x16x32_bf16 v[62:65], v[160:163], v[176:179], 0
	v_mfma_f32_16x16x32_bf16 v[54:57], v[168:171], v[176:179], 0
	v_mfma_f32_16x16x32_bf16 v[46:49], v[160:163], v[184:187], 0
	v_mfma_f32_16x16x32_bf16 v[38:41], v[168:171], v[184:187], 0
	v_mfma_f32_16x16x32_bf16 v[30:33], v[160:163], v[192:195], 0
	v_mfma_f32_16x16x32_bf16 v[22:25], v[168:171], v[192:195], 0
	v_mfma_f32_16x16x32_bf16 v[10:13], v[160:163], v[200:203], 0
	v_mfma_f32_16x16x32_bf16 v[2:5], v[168:171], v[200:203], 0
	v_mfma_f32_16x16x32_bf16 v[62:65], v[164:167], v[180:183], v[62:65]
	v_mfma_f32_16x16x32_bf16 v[54:57], v[172:175], v[180:183], v[54:57]
	v_mfma_f32_16x16x32_bf16 v[46:49], v[164:167], v[188:191], v[46:49]
	v_mfma_f32_16x16x32_bf16 v[38:41], v[172:175], v[188:191], v[38:41]
	v_mfma_f32_16x16x32_bf16 v[30:33], v[164:167], v[196:199], v[30:33]
	v_mfma_f32_16x16x32_bf16 v[22:25], v[172:175], v[196:199], v[22:25]
	v_mfma_f32_16x16x32_bf16 v[10:13], v[164:167], v[204:207], v[10:13]
	v_mfma_f32_16x16x32_bf16 v[2:5], v[172:175], v[204:207], v[2:5]
	s_setprio 0
	s_barrier
; #define PG8_STAGE(bufoff, gbase, voff) do { _Pragma("unroll") for (int _i = 0; _i < 2; ++_i) \
;         __builtin_amdgcn_global_load_lds((const unsigned*)((const char*)(gbase) + (voff)[_i]), (PG8_LAS unsigned*)(lds + (bufoff) + ldsw + _i * 8192), 16, 0, 0); } while (0)
; #define PG8_LDA(dst, b, h) do { _Pragma("unroll") for (int m = 0; m < 4; ++m) _Pragma("unroll") for (int k = 0; k < 2; ++k) dst[m][k] = *(const PG8_LAS bf16x8*)(lds + PG8_SA(b, h) + aoff + m * 2048 + k * 1024); } while (0)
; #define PG8_LDB(dst, b, h) do { _Pragma("unroll") for (int n = 0; n < 2; ++n) _Pragma("unroll") for (int k = 0; k < 2; ++k) dst[n][k] = *(const PG8_LAS bf16x8*)(lds + PG8_SB(b, h) + boff + n * 2048 + k * 1024); } while (0)
; #define PG8_MMA(ai, bj, At, Bt) do { __builtin_amdgcn_s_setprio(1); _Pragma("unroll") for (int m = 0; m < 4; ++m) _Pragma("unroll") for (int n = 0; n < 2; ++n) _Pragma("unroll") for (int k = 0; k < 2; ++k) \
;         acc[ai][bj][m][n] = __builtin_amdgcn_mfma_f32_16x16x32_bf16(Bt[n][k], At[m][k], acc[ai][bj][m][n], 0, 0, 0); __builtin_amdgcn_s_setprio(0); } while (0)
; #define PG8_WAIT_V(n) asm volatile("s_waitcnt vmcnt(" #n ")" ::: "memory")
; #define PG8_WAIT_L(n) asm volatile("s_waitcnt lgkmcnt(" #n ")" ::: "memory")
; #define PG8_BAR __builtin_amdgcn_s_barrier()
; #define PG8_SCHED __builtin_amdgcn_sched_barrier(0)
; template <class Epi, class Sched, bool ALIGN_EPI = false, bool SP2 = false>
; __device__ __forceinline__ void gemm_phase(PG8_LAS unsigned char* lds, const Gemm g, const Sched& S, const Epi& E) {
;     ...
;         for (int t = 0; t < nt; t += 2) {
;             const bool last = (t == nt - 2);
;             const char* a1 = cA + (size_t)(t + 1) * kstep;
;             const char* a2 = last ? nA : cA + (size_t)(t + 2) * kstep; const char* b2 = last ? nB : cB + (size_t)(t + 2) * kstep;
;     ...
;             PG8_LDB(B0, 1, 0); PG8_LDB(B1, 1, 1); PG8_SCHED; PG8_LDA(At, 1, 0); PG8_STAGE(PG8_SA(0, 1), a2 + hstep, voffA);
;             PG8_WAIT_V(8); PG8_WAIT_L(0); PG8_BAR; PG8_MMA(0, 0, At, B0); PG8_MMA(0, 1, At, B1); PG8_BAR; PG8_SCHED;
;             PG8_LDA(At, 1, 1); PG8_STAGE(PG8_SB(1, 0), b3, voffB); PG8_STAGE(PG8_SB(1, 1), b3 + hstep, voffB); PG8_STAGE(PG8_SA(1, 0), a3, voffA);
;             PG8_WAIT_V(8); PG8_WAIT_L(0); PG8_BAR; PG8_MMA(1, 0, At, B0); PG8_MMA(1, 1, At, B1); PG8_BAR; PG8_SCHED;
	s_add_i32 s47, 0, 0x18000
	s_add_i32 s92, 0, 0x1c000
	v_add_u32_e32 v156, s47, v1
	v_add_u32_e32 v172, s92, v1
	ds_read_b128 v[144:147], v156
	ds_read_b128 v[148:151], v156 offset:1024
	ds_read_b128 v[152:155], v156 offset:2048
	ds_read_b128 v[156:159], v156 offset:3072
	ds_read_b128 v[160:163], v172
	ds_read_b128 v[164:167], v172 offset:1024
	ds_read_b128 v[168:171], v172 offset:2048
	ds_read_b128 v[172:175], v172 offset:3072
	s_add_u32 s18, s38, 0x84000
	s_addc_u32 s19, s39, 0
	s_mov_b32 m0, s65
	ds_read_b128 v[176:179], v17 offset:32768
	ds_read_b128 v[180:183], v17 offset:33792
	ds_read_b128 v[184:187], v17 offset:34816
	ds_read_b128 v[188:191], v17 offset:35840
	ds_read_b128 v[192:195], v17 offset:36864
	ds_read_b128 v[196:199], v17 offset:37888
	ds_read_b128 v[200:203], v17 offset:38912
	ds_read_b128 v[204:207], v17 offset:39936
	global_load_lds_dwordx4 v138, s[18:19]
	s_mov_b32 m0, s68
	s_nop 0
	global_load_lds_dwordx4 v134, s[18:19]
	s_waitcnt vmcnt(8)
	s_waitcnt lgkmcnt(0)
	s_barrier
	s_setprio 1
	s_waitcnt lgkmcnt(0)
	v_mfma_f32_16x16x32_bf16 v[130:133], v[144:147], v[176:179], v[130:133]
	v_mfma_f32_16x16x32_bf16 v[122:125], v[152:155], v[176:179], v[122:125]
	v_mfma_f32_16x16x32_bf16 v[114:117], v[144:147], v[184:187], v[114:117]
	v_mfma_f32_16x16x32_bf16 v[106:109], v[152:155], v[184:187], v[106:109]
	v_mfma_f32_16x16x32_bf16 v[98:101], v[144:147], v[192:195], v[98:101]
	v_mfma_f32_16x16x32_bf16 v[90:93], v[152:155], v[192:195], v[90:93]
	v_mfma_f32_16x16x32_bf16 v[82:85], v[144:147], v[200:203], v[82:85]
	v_mfma_f32_16x16x32_bf16 v[74:77], v[152:155], v[200:203], v[74:77]
	v_mfma_f32_16x16x32_bf16 v[130:133], v[148:151], v[180:183], v[130:133]
	v_mfma_f32_16x16x32_bf16 v[122:125], v[156:159], v[180:183], v[122:125]
	v_mfma_f32_16x16x32_bf16 v[114:117], v[148:151], v[188:191], v[114:117]
	v_mfma_f32_16x16x32_bf16 v[106:109], v[156:159], v[188:191], v[106:109]
	v_mfma_f32_16x16x32_bf16 v[98:101], v[148:151], v[196:199], v[98:101]
	v_mfma_f32_16x16x32_bf16 v[90:93], v[156:159], v[196:199], v[90:93]
	v_mfma_f32_16x16x32_bf16 v[82:85], v[148:151], v[204:207], v[82:85]
	v_mfma_f32_16x16x32_bf16 v[74:77], v[156:159], v[204:207], v[74:77]
	s_setprio 0
	s_setprio 1
	v_mfma_f32_16x16x32_bf16 v[126:129], v[160:163], v[176:179], v[126:129]
	v_mfma_f32_16x16x32_bf16 v[118:121], v[168:171], v[176:179], v[118:121]
	v_mfma_f32_16x16x32_bf16 v[110:113], v[160:163], v[184:187], v[110:113]
	v_mfma_f32_16x16x32_bf16 v[102:105], v[168:171], v[184:187], v[102:105]
	v_mfma_f32_16x16x32_bf16 v[94:97], v[160:163], v[192:195], v[94:97]
	v_mfma_f32_16x16x32_bf16 v[86:89], v[168:171], v[192:195], v[86:89]
	v_mfma_f32_16x16x32_bf16 v[78:81], v[160:163], v[200:203], v[78:81]
	v_mfma_f32_16x16x32_bf16 v[70:73], v[168:171], v[200:203], v[70:73]
	v_mfma_f32_16x16x32_bf16 v[126:129], v[164:167], v[180:183], v[126:129]
	v_mfma_f32_16x16x32_bf16 v[118:121], v[172:175], v[180:183], v[118:121]
	v_mfma_f32_16x16x32_bf16 v[110:113], v[164:167], v[188:191], v[110:113]
	v_mfma_f32_16x16x32_bf16 v[102:105], v[172:175], v[188:191], v[102:105]
	v_mfma_f32_16x16x32_bf16 v[94:97], v[164:167], v[196:199], v[94:97]
	v_mfma_f32_16x16x32_bf16 v[86:89], v[172:175], v[196:199], v[86:89]
	v_mfma_f32_16x16x32_bf16 v[78:81], v[164:167], v[204:207], v[78:81]
	v_mfma_f32_16x16x32_bf16 v[70:73], v[172:175], v[204:207], v[70:73]
	s_setprio 0
	s_barrier
	s_add_i32 s18, s47, s46
	s_add_u32 s4, s4, 0x80
	s_addc_u32 s5, s5, 0
	s_mov_b32 m0, s18
	ds_read_b128 v[176:179], v17 offset:49152
	ds_read_b128 v[180:183], v17 offset:50176
	ds_read_b128 v[184:187], v17 offset:51200
	ds_read_b128 v[188:191], v17 offset:52224
	ds_read_b128 v[192:195], v17 offset:53248
	ds_read_b128 v[196:199], v17 offset:54272
	ds_read_b128 v[200:203], v17 offset:55296
	ds_read_b128 v[204:207], v17 offset:56320
	global_load_lds_dwordx4 v136, s[4:5]
	s_add_i32 m0, s18, 0x2000
	s_add_i32 s18, s92, s46
	global_load_lds_dwordx4 v14, s[4:5]
	s_add_u32 s4, s4, 0x84000
	s_addc_u32 s5, s5, 0
	s_mov_b32 m0, s18
	s_nop 0
	global_load_lds_dwordx4 v136, s[4:5]
	s_add_i32 m0, s18, 0x2000
	s_nop 0
	global_load_lds_dwordx4 v14, s[4:5]
	s_add_i32 m0, s54, 0x7f80
	s_nop 0
	global_load_lds_dwordx4 v138, s[38:39] offset:128
	s_add_i32 m0, s54, 0x9f80
	s_nop 0
	global_load_lds_dwordx4 v134, s[38:39] offset:128
	s_waitcnt vmcnt(8)
	s_waitcnt lgkmcnt(0)
	s_barrier
	s_setprio 1
	s_waitcnt lgkmcnt(0)
	v_mfma_f32_16x16x32_bf16 v[66:69], v[144:147], v[176:179], v[66:69]
	v_mfma_f32_16x16x32_bf16 v[58:61], v[152:155], v[176:179], v[58:61]
	v_mfma_f32_16x16x32_bf16 v[50:53], v[144:147], v[184:187], v[50:53]
	v_mfma_f32_16x16x32_bf16 v[42:45], v[152:155], v[184:187], v[42:45]
	v_mfma_f32_16x16x32_bf16 v[34:37], v[144:147], v[192:195], v[34:37]
	v_mfma_f32_16x16x32_bf16 v[26:29], v[152:155], v[192:195], v[26:29]
	v_mfma_f32_16x16x32_bf16 v[18:21], v[144:147], v[200:203], v[18:21]
	v_mfma_f32_16x16x32_bf16 v[6:9], v[152:155], v[200:203], v[6:9]
	v_mfma_f32_16x16x32_bf16 v[66:69], v[148:151], v[180:183], v[66:69]
	v_mfma_f32_16x16x32_bf16 v[58:61], v[156:159], v[180:183], v[58:61]
	v_mfma_f32_16x16x32_bf16 v[50:53], v[148:151], v[188:191], v[50:53]
	v_mfma_f32_16x16x32_bf16 v[42:45], v[156:159], v[188:191], v[42:45]
	v_mfma_f32_16x16x32_bf16 v[34:37], v[148:151], v[196:199], v[34:37]
	v_mfma_f32_16x16x32_bf16 v[26:29], v[156:159], v[196:199], v[26:29]
	v_mfma_f32_16x16x32_bf16 v[18:21], v[148:151], v[204:207], v[18:21]
	v_mfma_f32_16x16x32_bf16 v[6:9], v[156:159], v[204:207], v[6:9]
	s_setprio 0
	s_setprio 1
	v_mfma_f32_16x16x32_bf16 v[62:65], v[160:163], v[176:179], v[62:65]
	v_mfma_f32_16x16x32_bf16 v[54:57], v[168:171], v[176:179], v[54:57]
	v_mfma_f32_16x16x32_bf16 v[46:49], v[160:163], v[184:187], v[46:49]
	v_mfma_f32_16x16x32_bf16 v[38:41], v[168:171], v[184:187], v[38:41]
	v_mfma_f32_16x16x32_bf16 v[30:33], v[160:163], v[192:195], v[30:33]
	v_mfma_f32_16x16x32_bf16 v[22:25], v[168:171], v[192:195], v[22:25]
	v_mfma_f32_16x16x32_bf16 v[10:13], v[160:163], v[200:203], v[10:13]
	v_mfma_f32_16x16x32_bf16 v[2:5], v[168:171], v[200:203], v[2:5]
	v_mfma_f32_16x16x32_bf16 v[62:65], v[164:167], v[180:183], v[62:65]
	v_mfma_f32_16x16x32_bf16 v[54:57], v[172:175], v[180:183], v[54:57]
	v_mfma_f32_16x16x32_bf16 v[46:49], v[164:167], v[188:191], v[46:49]
	v_mfma_f32_16x16x32_bf16 v[38:41], v[172:175], v[188:191], v[38:41]
	v_mfma_f32_16x16x32_bf16 v[30:33], v[164:167], v[196:199], v[30:33]
	v_mfma_f32_16x16x32_bf16 v[22:25], v[172:175], v[196:199], v[22:25]
	v_mfma_f32_16x16x32_bf16 v[10:13], v[164:167], v[204:207], v[10:13]
	v_mfma_f32_16x16x32_bf16 v[2:5], v[172:175], v[204:207], v[2:5]
	s_setprio 0
	s_barrier
	s_add_i32 s43, s43, 2
	s_add_u32 s31, s31, 0x100
	s_addc_u32 s41, s41, 0
	s_cmp_gt_u32 s43, 29
	s_mov_b64 s[18:19], s[36:37]
	s_cbranch_scc0 .LBB0_402
	s_branch .Lgemm_exit_d
; #define PG8_STAGE(bufoff, gbase, voff) do { _Pragma("unroll") for (int _i = 0; _i < 2; ++_i) \
;         __builtin_amdgcn_global_load_lds((const unsigned*)((const char*)(gbase) + (voff)[_i]), (PG8_LAS unsigned*)(lds + (bufoff) + ldsw + _i * 8192), 16, 0, 0); } while (0)
; #define PG8_LDA(dst, b, h) do { _Pragma("unroll") for (int m = 0; m < 4; ++m) _Pragma("unroll") for (int k = 0; k < 2; ++k) dst[m][k] = *(const PG8_LAS bf16x8*)(lds + PG8_SA(b, h) + aoff + m * 2048 + k * 1024); } while (0)
; #define PG8_LDB(dst, b, h) do { _Pragma("unroll") for (int n = 0; n < 2; ++n) _Pragma("unroll") for (int k = 0; k < 2; ++k) dst[n][k] = *(const PG8_LAS bf16x8*)(lds + PG8_SB(b, h) + boff + n * 2048 + k * 1024); } while (0)
; #define PG8_MMA(ai, bj, At, Bt) do { __builtin_amdgcn_s_setprio(1); _Pragma("unroll") for (int m = 0; m < 4; ++m) _Pragma("unroll") for (int n = 0; n < 2; ++n) _Pragma("unroll") for (int k = 0; k < 2; ++k) \
;         acc[ai][bj][m][n] = __builtin_amdgcn_mfma_f32_16x16x32_bf16(Bt[n][k], At[m][k], acc[ai][bj][m][n], 0, 0, 0); __builtin_amdgcn_s_setprio(0); } while (0)
; #define PG8_WAIT_V(n) asm volatile("s_waitcnt vmcnt(" #n ")" ::: "memory")
; #define PG8_WAIT_L(n) asm volatile("s_waitcnt lgkmcnt(" #n ")" ::: "memory")
; #define PG8_BAR __builtin_amdgcn_s_barrier()
; #define PG8_SCHED __builtin_amdgcn_sched_barrier(0)
; template <class Epi, class Sched, bool ALIGN_EPI = false, bool SP2 = false>
; __device__ __forceinline__ void gemm_phase(PG8_LAS unsigned char* lds, const Gemm g, const Sched& S, const Epi& E) {
;     ...
;             if constexpr (SP2) {
;             PG8_LDB(B0, 0, 0); PG8_LDB(B1, 0, 1); PG8_SCHED; PG8_LDA(At, 0, 0); PG8_STAGE(PG8_SA(1, 1), a1 + hstep, voffA);
;             PG8_WAIT_V(8); PG8_WAIT_L(0); PG8_BAR; PG8_MMA(0, 0, At, B0); PG8_MMA(0, 1, At, B1); PG8_BAR; PG8_SCHED;
;             PG8_LDA(At, 0, 1); PG8_STAGE(PG8_SB(0, 0), b2, voffB); PG8_STAGE(PG8_SB(0, 1), b2 + hstep, voffB); PG8_STAGE(PG8_SA(0, 0), a2, voffA);
;             PG8_WAIT_V(8); PG8_WAIT_L(0); PG8_BAR; PG8_MMA(1, 0, At, B0); PG8_MMA(1, 1, At, B1); PG8_BAR; PG8_SCHED;
.Lpeel_rlx_d:
	s_add_u32 s36, s18, 0x100
	s_addc_u32 s37, s19, 0
	s_add_i32 s47, 0, 0x10000
	s_cmp_eq_u32 s43, 28
	s_cselect_b32 s39, s9, s37
	s_cselect_b32 s38, s8, s36
	s_cselect_b32 s5, s17, s41
	s_cselect_b32 s4, s16, s31
	s_add_i32 s92, 0, 0x14000
	v_add_u32_e32 v156, s47, v1
	v_add_u32_e32 v172, s92, v1
	ds_read_b128 v[144:147], v156
	ds_read_b128 v[148:151], v156 offset:1024
	ds_read_b128 v[152:155], v156 offset:2048
	ds_read_b128 v[156:159], v156 offset:3072
	ds_read_b128 v[160:163], v172
	ds_read_b128 v[164:167], v172 offset:1024
	ds_read_b128 v[168:171], v172 offset:2048
	ds_read_b128 v[172:175], v172 offset:3072
	s_add_i32 m0, s54, 0xc000
	ds_read_b128 v[176:179], v17
	ds_read_b128 v[180:183], v17 offset:1024
	ds_read_b128 v[184:187], v17 offset:2048
	ds_read_b128 v[188:191], v17 offset:3072
	ds_read_b128 v[192:195], v17 offset:4096
	ds_read_b128 v[196:199], v17 offset:5120
	ds_read_b128 v[200:203], v17 offset:6144
	ds_read_b128 v[204:207], v17 offset:7168
	global_load_lds_dwordx4 v142, s[18:19]
	s_add_i32 m0, s54, 0xe000
	s_nop 0
	global_load_lds_dwordx4 v140, s[18:19]
	s_waitcnt vmcnt(16)
	s_waitcnt lgkmcnt(0)
	s_barrier
	s_setprio 1
	s_waitcnt lgkmcnt(0)
	v_mfma_f32_16x16x32_bf16 v[130:133], v[144:147], v[176:179], 0
	v_mfma_f32_16x16x32_bf16 v[122:125], v[152:155], v[176:179], 0
	v_mfma_f32_16x16x32_bf16 v[114:117], v[144:147], v[184:187], 0
	v_mfma_f32_16x16x32_bf16 v[106:109], v[152:155], v[184:187], 0
	v_mfma_f32_16x16x32_bf16 v[98:101], v[144:147], v[192:195], 0
	v_mfma_f32_16x16x32_bf16 v[90:93], v[152:155], v[192:195], 0
	v_mfma_f32_16x16x32_bf16 v[82:85], v[144:147], v[200:203], 0
	v_mfma_f32_16x16x32_bf16 v[74:77], v[152:155], v[200:203], 0
	v_mfma_f32_16x16x32_bf16 v[130:133], v[148:151], v[180:183], v[130:133]
	v_mfma_f32_16x16x32_bf16 v[122:125], v[156:159], v[180:183], v[122:125]
	v_mfma_f32_16x16x32_bf16 v[114:117], v[148:151], v[188:191], v[114:117]
	v_mfma_f32_16x16x32_bf16 v[106:109], v[156:159], v[188:191], v[106:109]
	v_mfma_f32_16x16x32_bf16 v[98:101], v[148:151], v[196:199], v[98:101]
	v_mfma_f32_16x16x32_bf16 v[90:93], v[156:159], v[196:199], v[90:93]
	v_mfma_f32_16x16x32_bf16 v[82:85], v[148:151], v[204:207], v[82:85]
	v_mfma_f32_16x16x32_bf16 v[74:77], v[156:159], v[204:207], v[74:77]
	s_setprio 0
	s_setprio 1
	v_mfma_f32_16x16x32_bf16 v[126:129], v[160:163], v[176:179], 0
	v_mfma_f32_16x16x32_bf16 v[118:121], v[168:171], v[176:179], 0
	v_mfma_f32_16x16x32_bf16 v[110:113], v[160:163], v[184:187], 0
	v_mfma_f32_16x16x32_bf16 v[102:105], v[168:171], v[184:187], 0
	v_mfma_f32_16x16x32_bf16 v[94:97], v[160:163], v[192:195], 0
	v_mfma_f32_16x16x32_bf16 v[86:89], v[168:171], v[192:195], 0
	v_mfma_f32_16x16x32_bf16 v[78:81], v[160:163], v[200:203], 0
	v_mfma_f32_16x16x32_bf16 v[70:73], v[168:171], v[200:203], 0
	v_mfma_f32_16x16x32_bf16 v[126:129], v[164:167], v[180:183], v[126:129]
	v_mfma_f32_16x16x32_bf16 v[118:121], v[172:175], v[180:183], v[118:121]
	v_mfma_f32_16x16x32_bf16 v[110:113], v[164:167], v[188:191], v[110:113]
	v_mfma_f32_16x16x32_bf16 v[102:105], v[172:175], v[188:191], v[102:105]
	v_mfma_f32_16x16x32_bf16 v[94:97], v[164:167], v[196:199], v[94:97]
	v_mfma_f32_16x16x32_bf16 v[86:89], v[172:175], v[196:199], v[86:89]
	v_mfma_f32_16x16x32_bf16 v[78:81], v[164:167], v[204:207], v[78:81]
	v_mfma_f32_16x16x32_bf16 v[70:73], v[172:175], v[204:207], v[70:73]
	s_setprio 0
	s_barrier
	s_add_i32 s18, s47, s46
	s_mov_b32 m0, s18
	ds_read_b128 v[176:179], v17 offset:16384
	ds_read_b128 v[180:183], v17 offset:17408
	ds_read_b128 v[184:187], v17 offset:18432
	ds_read_b128 v[188:191], v17 offset:19456
	ds_read_b128 v[192:195], v17 offset:20480
	ds_read_b128 v[196:199], v17 offset:21504
	ds_read_b128 v[200:203], v17 offset:22528
	ds_read_b128 v[204:207], v17 offset:23552
	global_load_lds_dwordx4 v136, s[4:5]
	s_add_i32 m0, s18, 0x2000
	s_add_u32 s18, s4, 0x84000
	s_addc_u32 s19, s5, 0
	s_add_i32 s47, s92, s46
	global_load_lds_dwordx4 v14, s[4:5]
	s_mov_b32 m0, s47
	s_nop 0
	global_load_lds_dwordx4 v136, s[18:19]
	s_add_i32 m0, s47, 0x2000
	s_nop 0
	global_load_lds_dwordx4 v14, s[18:19]
	s_mov_b32 m0, s54
	s_nop 0
	global_load_lds_dwordx4 v138, s[38:39]
	s_mov_b32 m0, s64
	s_nop 0
	global_load_lds_dwordx4 v134, s[38:39]
	s_waitcnt vmcnt(16)
	s_waitcnt lgkmcnt(0)
	s_barrier
	s_setprio 1
	s_waitcnt lgkmcnt(0)
	v_mfma_f32_16x16x32_bf16 v[66:69], v[144:147], v[176:179], 0
	v_mfma_f32_16x16x32_bf16 v[58:61], v[152:155], v[176:179], 0
	v_mfma_f32_16x16x32_bf16 v[50:53], v[144:147], v[184:187], 0
	v_mfma_f32_16x16x32_bf16 v[42:45], v[152:155], v[184:187], 0
	v_mfma_f32_16x16x32_bf16 v[34:37], v[144:147], v[192:195], 0
	v_mfma_f32_16x16x32_bf16 v[26:29], v[152:155], v[192:195], 0
	v_mfma_f32_16x16x32_bf16 v[18:21], v[144:147], v[200:203], 0
	v_mfma_f32_16x16x32_bf16 v[6:9], v[152:155], v[200:203], 0
	v_mfma_f32_16x16x32_bf16 v[66:69], v[148:151], v[180:183], v[66:69]
	v_mfma_f32_16x16x32_bf16 v[58:61], v[156:159], v[180:183], v[58:61]
	v_mfma_f32_16x16x32_bf16 v[50:53], v[148:151], v[188:191], v[50:53]
	v_mfma_f32_16x16x32_bf16 v[42:45], v[156:159], v[188:191], v[42:45]
	v_mfma_f32_16x16x32_bf16 v[34:37], v[148:151], v[196:199], v[34:37]
	v_mfma_f32_16x16x32_bf16 v[26:29], v[156:159], v[196:199], v[26:29]
	v_mfma_f32_16x16x32_bf16 v[18:21], v[148:151], v[204:207], v[18:21]
	v_mfma_f32_16x16x32_bf16 v[6:9], v[156:159], v[204:207], v[6:9]
	s_setprio 0
	s_setprio 1
	v_mfma_f32_16x16x32_bf16 v[62:65], v[160:163], v[176:179], 0
	v_mfma_f32_16x16x32_bf16 v[54:57], v[168:171], v[176:179], 0
	v_mfma_f32_16x16x32_bf16 v[46:49], v[160:163], v[184:187], 0
	v_mfma_f32_16x16x32_bf16 v[38:41], v[168:171], v[184:187], 0
	v_mfma_f32_16x16x32_bf16 v[30:33], v[160:163], v[192:195], 0
	v_mfma_f32_16x16x32_bf16 v[22:25], v[168:171], v[192:195], 0
	v_mfma_f32_16x16x32_bf16 v[10:13], v[160:163], v[200:203], 0
	v_mfma_f32_16x16x32_bf16 v[2:5], v[168:171], v[200:203], 0
	v_mfma_f32_16x16x32_bf16 v[62:65], v[164:167], v[180:183], v[62:65]
	v_mfma_f32_16x16x32_bf16 v[54:57], v[172:175], v[180:183], v[54:57]
	v_mfma_f32_16x16x32_bf16 v[46:49], v[164:167], v[188:191], v[46:49]
	v_mfma_f32_16x16x32_bf16 v[38:41], v[172:175], v[188:191], v[38:41]
	v_mfma_f32_16x16x32_bf16 v[30:33], v[164:167], v[196:199], v[30:33]
	v_mfma_f32_16x16x32_bf16 v[22:25], v[172:175], v[196:199], v[22:25]
	v_mfma_f32_16x16x32_bf16 v[10:13], v[164:167], v[204:207], v[10:13]
	v_mfma_f32_16x16x32_bf16 v[2:5], v[172:175], v[204:207], v[2:5]
	s_setprio 0
	s_barrier
; #define PG8_STAGE(bufoff, gbase, voff) do { _Pragma("unroll") for (int _i = 0; _i < 2; ++_i) \
;         __builtin_amdgcn_global_load_lds((const unsigned*)((const char*)(gbase) + (voff)[_i]), (PG8_LAS unsigned*)(lds + (bufoff) + ldsw + _i * 8192), 16, 0, 0); } while (0)
; #define PG8_LDA(dst, b, h) do { _Pragma("unroll") for (int m = 0; m < 4; ++m) _Pragma("unroll") for (int k = 0; k < 2; ++k) dst[m][k] = *(const PG8_LAS bf16x8*)(lds + PG8_SA(b, h) + aoff + m * 2048 + k * 1024); } while (0)
; #define PG8_LDB(dst, b, h) do { _Pragma("unroll") for (int n = 0; n < 2; ++n) _Pragma("unroll") for (int k = 0; k < 2; ++k) dst[n][k] = *(const PG8_LAS bf16x8*)(lds + PG8_SB(b, h) + boff + n * 2048 + k * 1024); } while (0)
; #define PG8_MMA(ai, bj, At, Bt) do { __builtin_amdgcn_s_setprio(1); _Pragma("unroll") for (int m = 0; m < 4; ++m) _Pragma("unroll") for (int n = 0; n < 2; ++n) _Pragma("unroll") for (int k = 0; k < 2; ++k) \
;         acc[ai][bj][m][n] = __builtin_amdgcn_mfma_f32_16x16x32_bf16(Bt[n][k], At[m][k], acc[ai][bj][m][n], 0, 0, 0); __builtin_amdgcn_s_setprio(0); } while (0)
; #define PG8_WAIT_V(n) asm volatile("s_waitcnt vmcnt(" #n ")" ::: "memory")
; #define PG8_WAIT_L(n) asm volatile("s_waitcnt lgkmcnt(" #n ")" ::: "memory")
; #define PG8_BAR __builtin_amdgcn_s_barrier()
; #define PG8_SCHED __builtin_amdgcn_sched_barrier(0)
; template <class Epi, class Sched, bool ALIGN_EPI = false, bool SP2 = false>
; __device__ __forceinline__ void gemm_phase(PG8_LAS unsigned char* lds, const Gemm g, const Sched& S, const Epi& E) {
;     ...
;         for (int t = 0; t < nt; t += 2) {
;             const bool last = (t == nt - 2);
;             const char* a1 = cA + (size_t)(t + 1) * kstep;
;             const char* a2 = last ? nA : cA + (size_t)(t + 2) * kstep; const char* b2 = last ? nB : cB + (size_t)(t + 2) * kstep;
;     ...
;             PG8_LDB(B0, 1, 0); PG8_LDB(B1, 1, 1); PG8_SCHED; PG8_LDA(At, 1, 0); PG8_STAGE(PG8_SA(0, 1), a2 + hstep, voffA);
;             PG8_WAIT_V(8); PG8_WAIT_L(0); PG8_BAR; PG8_MMA(0, 0, At, B0); PG8_MMA(0, 1, At, B1); PG8_BAR; PG8_SCHED;
;             PG8_LDA(At, 1, 1); PG8_STAGE(PG8_SB(1, 0), b3, voffB); PG8_STAGE(PG8_SB(1, 1), b3 + hstep, voffB); PG8_STAGE(PG8_SA(1, 0), a3, voffA);
;             PG8_WAIT_V(8); PG8_WAIT_L(0); PG8_BAR; PG8_MMA(1, 0, At, B0); PG8_MMA(1, 1, At, B1); PG8_BAR; PG8_SCHED;
	s_add_i32 s47, 0, 0x18000
	s_add_i32 s92, 0, 0x1c000
	v_add_u32_e32 v156, s47, v1
	v_add_u32_e32 v172, s92, v1
	ds_read_b128 v[144:147], v156
	ds_read_b128 v[148:151], v156 offset:1024
	ds_read_b128 v[152:155], v156 offset:2048
	ds_read_b128 v[156:159], v156 offset:3072
	ds_read_b128 v[160:163], v172
	ds_read_b128 v[164:167], v172 offset:1024
	ds_read_b128 v[168:171], v172 offset:2048
	ds_read_b128 v[172:175], v172 offset:3072
	s_add_u32 s18, s38, 0x84000
	s_addc_u32 s19, s39, 0
	s_mov_b32 m0, s65
	ds_read_b128 v[176:179], v17 offset:32768
	ds_read_b128 v[180:183], v17 offset:33792
	ds_read_b128 v[184:187], v17 offset:34816
	ds_read_b128 v[188:191], v17 offset:35840
	ds_read_b128 v[192:195], v17 offset:36864
	ds_read_b128 v[196:199], v17 offset:37888
	ds_read_b128 v[200:203], v17 offset:38912
	ds_read_b128 v[204:207], v17 offset:39936
	global_load_lds_dwordx4 v138, s[18:19]
	s_mov_b32 m0, s68
	s_nop 0
	global_load_lds_dwordx4 v134, s[18:19]
	s_waitcnt vmcnt(8)
	s_waitcnt lgkmcnt(0)
	s_barrier
	s_setprio 1
	s_waitcnt lgkmcnt(0)
	v_mfma_f32_16x16x32_bf16 v[130:133], v[144:147], v[176:179], v[130:133]
	v_mfma_f32_16x16x32_bf16 v[122:125], v[152:155], v[176:179], v[122:125]
	v_mfma_f32_16x16x32_bf16 v[114:117], v[144:147], v[184:187], v[114:117]
	v_mfma_f32_16x16x32_bf16 v[106:109], v[152:155], v[184:187], v[106:109]
	v_mfma_f32_16x16x32_bf16 v[98:101], v[144:147], v[192:195], v[98:101]
	v_mfma_f32_16x16x32_bf16 v[90:93], v[152:155], v[192:195], v[90:93]
	v_mfma_f32_16x16x32_bf16 v[82:85], v[144:147], v[200:203], v[82:85]
	v_mfma_f32_16x16x32_bf16 v[74:77], v[152:155], v[200:203], v[74:77]
	v_mfma_f32_16x16x32_bf16 v[130:133], v[148:151], v[180:183], v[130:133]
	v_mfma_f32_16x16x32_bf16 v[122:125], v[156:159], v[180:183], v[122:125]
	v_mfma_f32_16x16x32_bf16 v[114:117], v[148:151], v[188:191], v[114:117]
	v_mfma_f32_16x16x32_bf16 v[106:109], v[156:159], v[188:191], v[106:109]
	v_mfma_f32_16x16x32_bf16 v[98:101], v[148:151], v[196:199], v[98:101]
	v_mfma_f32_16x16x32_bf16 v[90:93], v[156:159], v[196:199], v[90:93]
	v_mfma_f32_16x16x32_bf16 v[82:85], v[148:151], v[204:207], v[82:85]
	v_mfma_f32_16x16x32_bf16 v[74:77], v[156:159], v[204:207], v[74:77]
	s_setprio 0
	s_setprio 1
	v_mfma_f32_16x16x32_bf16 v[126:129], v[160:163], v[176:179], v[126:129]
	v_mfma_f32_16x16x32_bf16 v[118:121], v[168:171], v[176:179], v[118:121]
	v_mfma_f32_16x16x32_bf16 v[110:113], v[160:163], v[184:187], v[110:113]
	v_mfma_f32_16x16x32_bf16 v[102:105], v[168:171], v[184:187], v[102:105]
	v_mfma_f32_16x16x32_bf16 v[94:97], v[160:163], v[192:195], v[94:97]
	v_mfma_f32_16x16x32_bf16 v[86:89], v[168:171], v[192:195], v[86:89]
	v_mfma_f32_16x16x32_bf16 v[78:81], v[160:163], v[200:203], v[78:81]
	v_mfma_f32_16x16x32_bf16 v[70:73], v[168:171], v[200:203], v[70:73]
	v_mfma_f32_16x16x32_bf16 v[126:129], v[164:167], v[180:183], v[126:129]
	v_mfma_f32_16x16x32_bf16 v[118:121], v[172:175], v[180:183], v[118:121]
	v_mfma_f32_16x16x32_bf16 v[110:113], v[164:167], v[188:191], v[110:113]
	v_mfma_f32_16x16x32_bf16 v[102:105], v[172:175], v[188:191], v[102:105]
	v_mfma_f32_16x16x32_bf16 v[94:97], v[164:167], v[196:199], v[94:97]
	v_mfma_f32_16x16x32_bf16 v[86:89], v[172:175], v[196:199], v[86:89]
	v_mfma_f32_16x16x32_bf16 v[78:81], v[164:167], v[204:207], v[78:81]
	v_mfma_f32_16x16x32_bf16 v[70:73], v[172:175], v[204:207], v[70:73]
	s_setprio 0
	s_barrier
	s_add_i32 s18, s47, s46
	s_add_u32 s4, s4, 0x80
	s_addc_u32 s5, s5, 0
	s_mov_b32 m0, s18
	ds_read_b128 v[176:179], v17 offset:49152
	ds_read_b128 v[180:183], v17 offset:50176
	ds_read_b128 v[184:187], v17 offset:51200
	ds_read_b128 v[188:191], v17 offset:52224
	ds_read_b128 v[192:195], v17 offset:53248
	ds_read_b128 v[196:199], v17 offset:54272
	ds_read_b128 v[200:203], v17 offset:55296
	ds_read_b128 v[204:207], v17 offset:56320
	global_load_lds_dwordx4 v136, s[4:5]
	s_add_i32 m0, s18, 0x2000
	s_add_i32 s18, s92, s46
	global_load_lds_dwordx4 v14, s[4:5]
	s_add_u32 s4, s4, 0x84000
	s_addc_u32 s5, s5, 0
	s_mov_b32 m0, s18
	s_nop 0
	global_load_lds_dwordx4 v136, s[4:5]
	s_add_i32 m0, s18, 0x2000
	s_nop 0
	global_load_lds_dwordx4 v14, s[4:5]
	s_add_i32 m0, s54, 0x7f80
	s_nop 0
	global_load_lds_dwordx4 v138, s[38:39] offset:128
	s_add_i32 m0, s54, 0x9f80
	s_nop 0
	global_load_lds_dwordx4 v134, s[38:39] offset:128
	s_waitcnt vmcnt(8)
	s_waitcnt lgkmcnt(0)
	s_barrier
	s_setprio 1
	s_waitcnt lgkmcnt(0)
	v_mfma_f32_16x16x32_bf16 v[66:69], v[144:147], v[176:179], v[66:69]
	v_mfma_f32_16x16x32_bf16 v[58:61], v[152:155], v[176:179], v[58:61]
	v_mfma_f32_16x16x32_bf16 v[50:53], v[144:147], v[184:187], v[50:53]
	v_mfma_f32_16x16x32_bf16 v[42:45], v[152:155], v[184:187], v[42:45]
	v_mfma_f32_16x16x32_bf16 v[34:37], v[144:147], v[192:195], v[34:37]
	v_mfma_f32_16x16x32_bf16 v[26:29], v[152:155], v[192:195], v[26:29]
	v_mfma_f32_16x16x32_bf16 v[18:21], v[144:147], v[200:203], v[18:21]
	v_mfma_f32_16x16x32_bf16 v[6:9], v[152:155], v[200:203], v[6:9]
	v_mfma_f32_16x16x32_bf16 v[66:69], v[148:151], v[180:183], v[66:69]
	v_mfma_f32_16x16x32_bf16 v[58:61], v[156:159], v[180:183], v[58:61]
	v_mfma_f32_16x16x32_bf16 v[50:53], v[148:151], v[188:191], v[50:53]
	v_mfma_f32_16x16x32_bf16 v[42:45], v[156:159], v[188:191], v[42:45]
	v_mfma_f32_16x16x32_bf16 v[34:37], v[148:151], v[196:199], v[34:37]
	v_mfma_f32_16x16x32_bf16 v[26:29], v[156:159], v[196:199], v[26:29]
	v_mfma_f32_16x16x32_bf16 v[18:21], v[148:151], v[204:207], v[18:21]
	v_mfma_f32_16x16x32_bf16 v[6:9], v[156:159], v[204:207], v[6:9]
	s_setprio 0
	s_setprio 1
	v_mfma_f32_16x16x32_bf16 v[62:65], v[160:163], v[176:179], v[62:65]
	v_mfma_f32_16x16x32_bf16 v[54:57], v[168:171], v[176:179], v[54:57]
	v_mfma_f32_16x16x32_bf16 v[46:49], v[160:163], v[184:187], v[46:49]
	v_mfma_f32_16x16x32_bf16 v[38:41], v[168:171], v[184:187], v[38:41]
	v_mfma_f32_16x16x32_bf16 v[30:33], v[160:163], v[192:195], v[30:33]
	v_mfma_f32_16x16x32_bf16 v[22:25], v[168:171], v[192:195], v[22:25]
	v_mfma_f32_16x16x32_bf16 v[10:13], v[160:163], v[200:203], v[10:13]
	v_mfma_f32_16x16x32_bf16 v[2:5], v[168:171], v[200:203], v[2:5]
	v_mfma_f32_16x16x32_bf16 v[62:65], v[164:167], v[180:183], v[62:65]
	v_mfma_f32_16x16x32_bf16 v[54:57], v[172:175], v[180:183], v[54:57]
	v_mfma_f32_16x16x32_bf16 v[46:49], v[164:167], v[188:191], v[46:49]
	v_mfma_f32_16x16x32_bf16 v[38:41], v[172:175], v[188:191], v[38:41]
	v_mfma_f32_16x16x32_bf16 v[30:33], v[164:167], v[196:199], v[30:33]
	v_mfma_f32_16x16x32_bf16 v[22:25], v[172:175], v[196:199], v[22:25]
	v_mfma_f32_16x16x32_bf16 v[10:13], v[164:167], v[204:207], v[10:13]
	v_mfma_f32_16x16x32_bf16 v[2:5], v[172:175], v[204:207], v[2:5]
	s_setprio 0
	s_barrier
	s_add_i32 s43, s43, 2
	s_add_u32 s31, s31, 0x100
	s_addc_u32 s41, s41, 0
	s_cmp_gt_u32 s43, 29
	s_mov_b64 s[18:19], s[36:37]
	s_cbranch_scc0 .LBB0_402
	s_branch .Lgemm_exit_d
